# A/B: deferred-barrier epilogue overlap removed from FFI only (VALU-bound epilogue)
# baseline (speedup 1.0000x reference)
; #define G_STAGE(bufoff, gbase, o0, h64) do { \
;         __builtin_amdgcn_global_load_lds((const unsigned*)((const char*)(gbase) + (o0)), (LAS unsigned*)(lds + (bufoff) + ldsw), 16, 0, 0); \
;         __builtin_amdgcn_global_load_lds((const unsigned*)((const char*)(gbase) + (h64) + (o0)), (LAS unsigned*)(lds + (bufoff) + ldsw + 8192), 16, 0, 0); } while (0)
; #define G_LDA(dst, b, h) do { _Pragma("unroll") for (int m = 0; m < 4; ++m) _Pragma("unroll") for (int k = 0; k < 2; ++k) dst[m][k] = *(const LAS bf16x8*)(lds + G_SA(b, h) + aoff + m * 2048 + k * 1024); } while (0)
; #define G_LDB(dst, b, h) do { _Pragma("unroll") for (int n = 0; n < 2; ++n) _Pragma("unroll") for (int k = 0; k < 2; ++k) dst[n][k] = *(const LAS bf16x8*)(lds + G_SB(b, h) + boff + n * 2048 + k * 1024); } while (0)
; #define G_WAIT_L(n) asm volatile("s_waitcnt lgkmcnt(" #n ")" ::: "memory")
; #define G_BAR __builtin_amdgcn_s_barrier()
; #define G_SCHED __builtin_amdgcn_sched_barrier(0)
;     ...
;         for (int t = 0; t < nt; t += 2) {
;             const bool last = (t == nt - 2);
;             const char* a1 = cA + (size_t)(t + 1) * ckA;
;             const char* a2 = last ? nA : cA + (size_t)(t + 2) * ckA; const char* b2 = last ? nB : cB + (size_t)(t + 2) * kB;
;             const char* a3 = a2 + ckA; const char* b3 = b2 + kB;
;             G_LDB(B0, 0, 0); G_SCHED; G_LDA(At, 0, 0); G_STAGE(G_SA(1, 1), a1 + chA, cA0, qA);
;             G_WAIT_L(8); G_BAR; G_WAIT_L(0); G_MMA(0, 0, At, B0); G_BAR; G_SCHED;
;             G_LDB(B1, 0, 1); G_STAGE(G_SB(0, 0), b2, cB0, qB);
;             G_BAR; G_WAIT_L(0); G_MMA(0, 1, At, B1); G_BAR;
;             G_LDA(At, 0, 1); G_STAGE(G_SA(0, 0), a2, cA0, qA);
;             G_BAR; G_WAIT_L(0); G_MMA(1, 0, At, B0); G_BAR; G_SCHED;
.LBB0_1120:
	s_add_u32 s4, s2, 0xfffc0080
	s_addc_u32 s5, s3, -1
	s_add_i32 s19, 0, 0x10000
	v_add_u32_e32 v0, s19, v149
	ds_read_b128 v[140:143], v0
	ds_read_b128 v[144:147], v0 offset:1024
	ds_read_b128 v[152:155], v0 offset:2048
	ds_read_b128 v[156:159], v0 offset:3072
	s_cmp_eq_u32 s18, 12
	s_cselect_b32 s5, s13, s5
	s_cselect_b32 s4, s12, s4
	s_cselect_b32 s41, s15, s17
	s_cselect_b32 s40, s14, s16
	v_lshl_add_u64 v[184:185], s[2:3], 0, v[138:139]
	s_add_i32 m0, s26, 0xc000
	ds_read_b128 v[160:163], v150
	ds_read_b128 v[164:167], v150 offset:1024
	ds_read_b128 v[172:175], v150 offset:2048
	ds_read_b128 v[176:179], v150 offset:3072
	ds_read_b128 v[180:183], v150 offset:4096
	ds_read_b128 v[196:199], v150 offset:5120
	ds_read_b128 v[200:203], v150 offset:6144
	ds_read_b128 v[204:207], v150 offset:7168
	global_load_lds_dwordx4 v[184:185], off
	v_lshl_add_u64 v[184:185], v[184:185], 0, s[0:1]
	s_add_i32 m0, s26, 0xe000
	s_nop 0
	global_load_lds_dwordx4 v[184:185], off
	s_waitcnt lgkmcnt(8)
	s_barrier
	s_waitcnt lgkmcnt(0)
	v_mfma_f32_16x16x32_bf16 v[132:135], v[140:143], v[160:163], v[132:135]
	v_mfma_f32_16x16x32_bf16 v[124:127], v[152:155], v[160:163], v[124:127]
	v_mfma_f32_16x16x32_bf16 v[116:119], v[140:143], v[172:175], v[116:119]
	v_mfma_f32_16x16x32_bf16 v[108:111], v[152:155], v[172:175], v[108:111]
	v_mfma_f32_16x16x32_bf16 v[100:103], v[140:143], v[180:183], v[100:103]
	v_mfma_f32_16x16x32_bf16 v[92:95], v[152:155], v[180:183], v[92:95]
	v_mfma_f32_16x16x32_bf16 v[84:87], v[140:143], v[200:203], v[84:87]
	v_mfma_f32_16x16x32_bf16 v[76:79], v[152:155], v[200:203], v[76:79]
	v_mfma_f32_16x16x32_bf16 v[132:135], v[144:147], v[164:167], v[132:135]
	v_mfma_f32_16x16x32_bf16 v[124:127], v[156:159], v[164:167], v[124:127]
	v_mfma_f32_16x16x32_bf16 v[116:119], v[144:147], v[176:179], v[116:119]
	v_mfma_f32_16x16x32_bf16 v[108:111], v[156:159], v[176:179], v[108:111]
	v_mfma_f32_16x16x32_bf16 v[100:103], v[144:147], v[196:199], v[100:103]
	v_mfma_f32_16x16x32_bf16 v[92:95], v[156:159], v[196:199], v[92:95]
	v_mfma_f32_16x16x32_bf16 v[84:87], v[144:147], v[204:207], v[84:87]
	v_mfma_f32_16x16x32_bf16 v[76:79], v[156:159], v[204:207], v[76:79]
	s_barrier
	s_add_i32 s39, 0, 0x14000
	s_add_i32 s19, s19, s21
	v_add_u32_e32 v0, s39, v149
	v_lshl_add_u64 v[184:185], s[40:41], 0, v[2:3]
	s_mov_b32 m0, s19
	ds_read_b128 v[208:211], v0
	ds_read_b128 v[212:215], v0 offset:1024
	ds_read_b128 v[216:219], v0 offset:2048
	ds_read_b128 v[220:223], v0 offset:3072
	global_load_lds_dwordx4 v[184:185], off
	v_lshl_add_u64 v[224:225], v[184:185], 0, s[0:1]
	s_add_i32 m0, s19, 0x2000
	s_nop 0
	global_load_lds_dwordx4 v[224:225], off
	s_barrier
	s_waitcnt lgkmcnt(0)
	v_mfma_f32_16x16x32_bf16 v[128:131], v[208:211], v[160:163], v[128:131]
	v_mfma_f32_16x16x32_bf16 v[120:123], v[216:219], v[160:163], v[120:123]
	v_mfma_f32_16x16x32_bf16 v[112:115], v[208:211], v[172:175], v[112:115]
	v_mfma_f32_16x16x32_bf16 v[104:107], v[216:219], v[172:175], v[104:107]
	v_mfma_f32_16x16x32_bf16 v[96:99], v[208:211], v[180:183], v[96:99]
	v_mfma_f32_16x16x32_bf16 v[88:91], v[216:219], v[180:183], v[88:91]
	v_mfma_f32_16x16x32_bf16 v[80:83], v[208:211], v[200:203], v[80:83]
	v_mfma_f32_16x16x32_bf16 v[72:75], v[216:219], v[200:203], v[72:75]
	v_mfma_f32_16x16x32_bf16 v[128:131], v[212:215], v[164:167], v[128:131]
	v_mfma_f32_16x16x32_bf16 v[120:123], v[220:223], v[164:167], v[120:123]
	v_mfma_f32_16x16x32_bf16 v[112:115], v[212:215], v[176:179], v[112:115]
	v_mfma_f32_16x16x32_bf16 v[104:107], v[220:223], v[176:179], v[104:107]
	v_mfma_f32_16x16x32_bf16 v[96:99], v[212:215], v[196:199], v[96:99]
	v_mfma_f32_16x16x32_bf16 v[88:91], v[220:223], v[196:199], v[88:91]
	v_mfma_f32_16x16x32_bf16 v[80:83], v[212:215], v[204:207], v[80:83]
	v_mfma_f32_16x16x32_bf16 v[72:75], v[220:223], v[204:207], v[72:75]
	s_barrier
	s_mov_b32 m0, s26
	v_lshl_add_u64 v[224:225], s[4:5], 0, v[136:137]
	ds_read_b128 v[160:163], v150 offset:16384
	ds_read_b128 v[164:167], v150 offset:17408
	ds_read_b128 v[172:175], v150 offset:18432
	ds_read_b128 v[176:179], v150 offset:19456
	ds_read_b128 v[180:183], v150 offset:20480
	ds_read_b128 v[196:199], v150 offset:21504
	ds_read_b128 v[200:203], v150 offset:22528
	ds_read_b128 v[204:207], v150 offset:23552
	global_load_lds_dwordx4 v[224:225], off
	v_lshl_add_u64 v[226:227], v[224:225], 0, s[0:1]
	s_mov_b32 m0, s27
	s_nop 0
	global_load_lds_dwordx4 v[226:227], off
	s_barrier
	s_waitcnt lgkmcnt(0)
	v_mfma_f32_16x16x32_bf16 v[68:71], v[140:143], v[160:163], v[68:71]
	v_mfma_f32_16x16x32_bf16 v[60:63], v[152:155], v[160:163], v[60:63]
	v_mfma_f32_16x16x32_bf16 v[52:55], v[140:143], v[172:175], v[52:55]
	v_mfma_f32_16x16x32_bf16 v[44:47], v[152:155], v[172:175], v[44:47]
	v_mfma_f32_16x16x32_bf16 v[36:39], v[140:143], v[180:183], v[36:39]
	v_mfma_f32_16x16x32_bf16 v[28:31], v[152:155], v[180:183], v[28:31]
	v_mfma_f32_16x16x32_bf16 v[20:23], v[140:143], v[200:203], v[20:23]
	v_mfma_f32_16x16x32_bf16 v[12:15], v[152:155], v[200:203], v[12:15]
	v_mfma_f32_16x16x32_bf16 v[68:71], v[144:147], v[164:167], v[68:71]
	v_mfma_f32_16x16x32_bf16 v[60:63], v[156:159], v[164:167], v[60:63]
	v_mfma_f32_16x16x32_bf16 v[52:55], v[144:147], v[176:179], v[52:55]
	v_mfma_f32_16x16x32_bf16 v[44:47], v[156:159], v[176:179], v[44:47]
	v_mfma_f32_16x16x32_bf16 v[36:39], v[144:147], v[196:199], v[36:39]
	v_mfma_f32_16x16x32_bf16 v[28:31], v[156:159], v[196:199], v[28:31]
	v_mfma_f32_16x16x32_bf16 v[20:23], v[144:147], v[204:207], v[20:23]
	v_mfma_f32_16x16x32_bf16 v[12:15], v[156:159], v[204:207], v[12:15]
	s_barrier
; #define G_STAGE(bufoff, gbase, o0, h64) do { \
;         __builtin_amdgcn_global_load_lds((const unsigned*)((const char*)(gbase) + (o0)), (LAS unsigned*)(lds + (bufoff) + ldsw), 16, 0, 0); \
;         __builtin_amdgcn_global_load_lds((const unsigned*)((const char*)(gbase) + (h64) + (o0)), (LAS unsigned*)(lds + (bufoff) + ldsw + 8192), 16, 0, 0); } while (0)
; #define G_LDA(dst, b, h) do { _Pragma("unroll") for (int m = 0; m < 4; ++m) _Pragma("unroll") for (int k = 0; k < 2; ++k) dst[m][k] = *(const LAS bf16x8*)(lds + G_SA(b, h) + aoff + m * 2048 + k * 1024); } while (0)
; #define G_LDB(dst, b, h) do { _Pragma("unroll") for (int n = 0; n < 2; ++n) _Pragma("unroll") for (int k = 0; k < 2; ++k) dst[n][k] = *(const LAS bf16x8*)(lds + G_SB(b, h) + boff + n * 2048 + k * 1024); } while (0)
; #define G_WAIT_V(n) asm volatile("s_waitcnt vmcnt(" #n ")" ::: "memory")
; #define G_WAIT_L(n) asm volatile("s_waitcnt lgkmcnt(" #n ")" ::: "memory")
; #define G_BAR __builtin_amdgcn_s_barrier()
; #define G_SCHED __builtin_amdgcn_sched_barrier(0)
;     ...
;             G_STAGE(G_SB(0, 1), b2 + chB, cB0, qB);
;             G_WAIT_V(6); G_BAR; G_MMA(1, 1, At, B1); G_BAR;
;             G_LDB(B0, 1, 0); G_SCHED; G_LDA(At, 1, 0); G_STAGE(G_SA(0, 1), a2 + chA, cA0, qA);
;             G_WAIT_L(8); G_BAR; G_WAIT_L(0); G_MMA(0, 0, At, B0); G_BAR; G_SCHED;
;             G_LDB(B1, 1, 1); G_STAGE(G_SB(1, 0), b3, cB0, qB);
;             G_BAR; G_WAIT_L(0); G_MMA(0, 1, At, B1); G_BAR;
;             G_LDA(At, 1, 1); G_STAGE(G_SA(1, 0), a3, cA0, qA);
;             G_BAR; G_WAIT_L(0); G_MMA(1, 0, At, B0); G_BAR; G_SCHED;
	s_add_i32 s4, s39, s21
	v_lshl_add_u64 v[140:141], v[184:185], 0, s[42:43]
	s_mov_b32 m0, s4
	s_nop 0
	global_load_lds_dwordx4 v[140:141], off
	v_lshl_add_u64 v[140:141], v[184:185], 0, s[50:51]
	s_add_i32 m0, s4, 0x2000
	s_nop 0
	global_load_lds_dwordx4 v[140:141], off
	s_waitcnt vmcnt(6)
	s_barrier
	v_mfma_f32_16x16x32_bf16 v[64:67], v[208:211], v[160:163], v[64:67]
	v_mfma_f32_16x16x32_bf16 v[56:59], v[216:219], v[160:163], v[56:59]
	v_mfma_f32_16x16x32_bf16 v[48:51], v[208:211], v[172:175], v[48:51]
	v_mfma_f32_16x16x32_bf16 v[40:43], v[216:219], v[172:175], v[40:43]
	v_mfma_f32_16x16x32_bf16 v[32:35], v[208:211], v[180:183], v[32:35]
	v_mfma_f32_16x16x32_bf16 v[24:27], v[216:219], v[180:183], v[24:27]
	v_mfma_f32_16x16x32_bf16 v[16:19], v[208:211], v[200:203], v[16:19]
	v_mfma_f32_16x16x32_bf16 v[8:11], v[216:219], v[200:203], v[8:11]
	v_mfma_f32_16x16x32_bf16 v[64:67], v[212:215], v[164:167], v[64:67]
	v_mfma_f32_16x16x32_bf16 v[56:59], v[220:223], v[164:167], v[56:59]
	v_mfma_f32_16x16x32_bf16 v[48:51], v[212:215], v[176:179], v[48:51]
	v_mfma_f32_16x16x32_bf16 v[40:43], v[220:223], v[176:179], v[40:43]
	v_mfma_f32_16x16x32_bf16 v[32:35], v[212:215], v[196:199], v[32:35]
	v_mfma_f32_16x16x32_bf16 v[24:27], v[220:223], v[196:199], v[24:27]
	v_mfma_f32_16x16x32_bf16 v[16:19], v[212:215], v[204:207], v[16:19]
	v_mfma_f32_16x16x32_bf16 v[8:11], v[220:223], v[204:207], v[8:11]
	s_barrier
	s_add_i32 s4, 0, 0x18000
	v_add_u32_e32 v0, s4, v149
	ds_read_b128 v[140:143], v0
	ds_read_b128 v[144:147], v0 offset:1024
	ds_read_b128 v[152:155], v0 offset:2048
	ds_read_b128 v[156:159], v0 offset:3072
	s_mov_b32 m0, s29
	v_lshl_add_u64 v[208:209], v[224:225], 0, s[42:43]
	ds_read_b128 v[160:163], v150 offset:32768
	ds_read_b128 v[164:167], v150 offset:33792
	ds_read_b128 v[172:175], v150 offset:34816
	ds_read_b128 v[176:179], v150 offset:35840
	ds_read_b128 v[180:183], v150 offset:36864
	ds_read_b128 v[196:199], v150 offset:37888
	ds_read_b128 v[200:203], v150 offset:38912
	ds_read_b128 v[204:207], v150 offset:39936
	global_load_lds_dwordx4 v[208:209], off
	v_lshl_add_u64 v[208:209], v[224:225], 0, s[50:51]
	s_mov_b32 m0, s30
	s_nop 0
	global_load_lds_dwordx4 v[208:209], off
	s_waitcnt lgkmcnt(8)
	s_barrier
	s_waitcnt lgkmcnt(0)
	v_mfma_f32_16x16x32_bf16 v[132:135], v[140:143], v[160:163], v[132:135]
	v_mfma_f32_16x16x32_bf16 v[124:127], v[152:155], v[160:163], v[124:127]
	v_mfma_f32_16x16x32_bf16 v[116:119], v[140:143], v[172:175], v[116:119]
	v_mfma_f32_16x16x32_bf16 v[108:111], v[152:155], v[172:175], v[108:111]
	v_mfma_f32_16x16x32_bf16 v[100:103], v[140:143], v[180:183], v[100:103]
	v_mfma_f32_16x16x32_bf16 v[92:95], v[152:155], v[180:183], v[92:95]
	v_mfma_f32_16x16x32_bf16 v[84:87], v[140:143], v[200:203], v[84:87]
	v_mfma_f32_16x16x32_bf16 v[76:79], v[152:155], v[200:203], v[76:79]
	v_mfma_f32_16x16x32_bf16 v[132:135], v[144:147], v[164:167], v[132:135]
	v_mfma_f32_16x16x32_bf16 v[124:127], v[156:159], v[164:167], v[124:127]
	v_mfma_f32_16x16x32_bf16 v[116:119], v[144:147], v[176:179], v[116:119]
	v_mfma_f32_16x16x32_bf16 v[108:111], v[156:159], v[176:179], v[108:111]
	v_mfma_f32_16x16x32_bf16 v[100:103], v[144:147], v[196:199], v[100:103]
	v_mfma_f32_16x16x32_bf16 v[92:95], v[156:159], v[196:199], v[92:95]
	v_mfma_f32_16x16x32_bf16 v[84:87], v[144:147], v[204:207], v[84:87]
	v_mfma_f32_16x16x32_bf16 v[76:79], v[156:159], v[204:207], v[76:79]
	s_barrier
	s_add_i32 s5, 0, 0x1c000
	s_add_i32 s4, s4, s21
	v_add_u32_e32 v0, s5, v149
	v_lshl_add_u64 v[226:227], v[184:185], 0, s[46:47]
	s_mov_b32 m0, s4
	ds_read_b128 v[208:211], v0
	ds_read_b128 v[212:215], v0 offset:1024
	ds_read_b128 v[216:219], v0 offset:2048
	ds_read_b128 v[220:223], v0 offset:3072
	global_load_lds_dwordx4 v[226:227], off
	v_lshl_add_u64 v[226:227], v[184:185], 0, s[52:53]
	s_add_i32 m0, s4, 0x2000
	s_nop 0
	global_load_lds_dwordx4 v[226:227], off
	s_barrier
	s_waitcnt lgkmcnt(0)
	v_mfma_f32_16x16x32_bf16 v[128:131], v[208:211], v[160:163], v[128:131]
	v_mfma_f32_16x16x32_bf16 v[120:123], v[216:219], v[160:163], v[120:123]
	v_mfma_f32_16x16x32_bf16 v[112:115], v[208:211], v[172:175], v[112:115]
	v_mfma_f32_16x16x32_bf16 v[104:107], v[216:219], v[172:175], v[104:107]
	v_mfma_f32_16x16x32_bf16 v[96:99], v[208:211], v[180:183], v[96:99]
	v_mfma_f32_16x16x32_bf16 v[88:91], v[216:219], v[180:183], v[88:91]
	v_mfma_f32_16x16x32_bf16 v[80:83], v[208:211], v[200:203], v[80:83]
	v_mfma_f32_16x16x32_bf16 v[72:75], v[216:219], v[200:203], v[72:75]
	v_mfma_f32_16x16x32_bf16 v[128:131], v[212:215], v[164:167], v[128:131]
	v_mfma_f32_16x16x32_bf16 v[120:123], v[220:223], v[164:167], v[120:123]
	v_mfma_f32_16x16x32_bf16 v[112:115], v[212:215], v[176:179], v[112:115]
	v_mfma_f32_16x16x32_bf16 v[104:107], v[220:223], v[176:179], v[104:107]
	v_mfma_f32_16x16x32_bf16 v[96:99], v[212:215], v[196:199], v[96:99]
	v_mfma_f32_16x16x32_bf16 v[88:91], v[220:223], v[196:199], v[88:91]
	v_mfma_f32_16x16x32_bf16 v[80:83], v[212:215], v[204:207], v[80:83]
	v_mfma_f32_16x16x32_bf16 v[72:75], v[220:223], v[204:207], v[72:75]
	s_barrier
	s_mov_b32 m0, s31
	v_lshl_add_u64 v[226:227], v[224:225], 0, s[46:47]
	ds_read_b128 v[160:163], v150 offset:49152
	ds_read_b128 v[164:167], v150 offset:50176
	ds_read_b128 v[172:175], v150 offset:51200
	ds_read_b128 v[176:179], v150 offset:52224
	ds_read_b128 v[180:183], v150 offset:53248
	ds_read_b128 v[196:199], v150 offset:54272
	ds_read_b128 v[200:203], v150 offset:55296
	ds_read_b128 v[204:207], v150 offset:56320
	global_load_lds_dwordx4 v[226:227], off
	v_lshl_add_u64 v[224:225], v[224:225], 0, s[52:53]
	s_mov_b32 m0, s34
	s_nop 0
	global_load_lds_dwordx4 v[224:225], off
	s_barrier
; __device__ __forceinline__ float sigmoidf_(float v) { return __builtin_amdgcn_rcpf(1.0f + __expf(-v)); }
; __device__ __forceinline__ u32x4 pack8(const f32x4 a, const f32x4 b) { u32x4 w; w.x = cvt_pk_bf16(a[0], a[1]); w.y = cvt_pk_bf16(a[2], a[3]); w.z = cvt_pk_bf16(b[0], b[1]); w.w = cvt_pk_bf16(b[2], b[3]); return w; }
; #define MEMFENCE asm volatile("" ::: "memory")
; #define G_STAGE(bufoff, gbase, o0, h64) do { \
;         __builtin_amdgcn_global_load_lds((const unsigned*)((const char*)(gbase) + (o0)), (LAS unsigned*)(lds + (bufoff) + ldsw), 16, 0, 0); \
;         __builtin_amdgcn_global_load_lds((const unsigned*)((const char*)(gbase) + (h64) + (o0)), (LAS unsigned*)(lds + (bufoff) + ldsw + 8192), 16, 0, 0); } while (0)
; #define G_WAIT_V(n) asm volatile("s_waitcnt vmcnt(" #n ")" ::: "memory")
; #define G_WAIT_L(n) asm volatile("s_waitcnt lgkmcnt(" #n ")" ::: "memory")
; #define G_BAR __builtin_amdgcn_s_barrier()
; #define G_SCHED __builtin_amdgcn_sched_barrier(0)
;     template <int KIND> __device__ __forceinline__ void run(f32x4 (&acc)[2][2][4][2], const Unit& u, int tid_in) const {
;     ...
;         if constexpr (KIND == K_FFI) { bf16_t* act = zb; float rs[8]; get_rs(u, wr, fr, rs);
; #pragma unroll
;             for (int ai = 0; ai < 2; ++ai)
; #pragma unroll
;                 for (int m = 0; m < 4; ++m) { int row = rbase + ai * 128 + m * 16; asm volatile("" : "+v"(row)); const float r = rs[ai * 4 + m]; f32x4 o[2];
; #pragma unroll
;                     for (int n = 0; n < 2; ++n) { const f32x4 g = acc[ai][0][m][n] * r, v = acc[ai][1][m][n] * r;
; #pragma unroll
;                         for (int j = 0; j < 4; ++j) o[n][j] = g[j] * sigmoidf_(g[j]) * v[j]; }
;                     *(u32x4*)(act + (size_t)row * ZW + u.pn * 128 + cl) = pack8(o[0], o[1]); MEMFENCE; }
;     ...
;             G_BAR; G_WAIT_L(0); G_MMA(1, 0, At, B0); G_BAR; G_SCHED;
;             G_STAGE(G_SB(1, 1), b3 + chB, cB0, qB);
;             G_WAIT_V(6); G_BAR; G_MMA(1, 1, At, B1); G_BAR;
;         }
	s_waitcnt lgkmcnt(0)
	v_mfma_f32_16x16x32_bf16 v[68:71], v[140:143], v[160:163], v[68:71]
	v_mfma_f32_16x16x32_bf16 v[60:63], v[152:155], v[160:163], v[60:63]
	v_mfma_f32_16x16x32_bf16 v[52:55], v[140:143], v[172:175], v[52:55]
	v_mfma_f32_16x16x32_bf16 v[44:47], v[152:155], v[172:175], v[44:47]
	v_mfma_f32_16x16x32_bf16 v[36:39], v[140:143], v[180:183], v[36:39]
	v_mfma_f32_16x16x32_bf16 v[28:31], v[152:155], v[180:183], v[28:31]
	v_mfma_f32_16x16x32_bf16 v[20:23], v[140:143], v[200:203], v[20:23]
	v_mfma_f32_16x16x32_bf16 v[12:15], v[152:155], v[200:203], v[12:15]
	v_mfma_f32_16x16x32_bf16 v[68:71], v[144:147], v[164:167], v[68:71]
	v_mfma_f32_16x16x32_bf16 v[60:63], v[156:159], v[164:167], v[60:63]
	v_mfma_f32_16x16x32_bf16 v[52:55], v[144:147], v[176:179], v[52:55]
	v_mfma_f32_16x16x32_bf16 v[44:47], v[156:159], v[176:179], v[44:47]
	v_mfma_f32_16x16x32_bf16 v[36:39], v[144:147], v[196:199], v[36:39]
	v_mfma_f32_16x16x32_bf16 v[28:31], v[156:159], v[196:199], v[28:31]
	v_mfma_f32_16x16x32_bf16 v[20:23], v[144:147], v[204:207], v[20:23]
	v_mfma_f32_16x16x32_bf16 v[12:15], v[156:159], v[204:207], v[12:15]
	s_barrier
	s_add_i32 s4, s5, s21
	v_lshl_add_u64 v[140:141], v[184:185], 0, s[54:55]
	s_mov_b32 m0, s4
	s_nop 0
	global_load_lds_dwordx4 v[140:141], off
	v_lshl_add_u64 v[140:141], v[184:185], 0, s[58:59]
	s_add_i32 m0, s4, 0x2000
	s_nop 0
	global_load_lds_dwordx4 v[140:141], off
	s_add_i32 s18, s18, 2
	s_add_u32 s2, s2, 0x100
	s_addc_u32 s3, s3, 0
	s_add_u32 s16, s16, 0x100
	s_addc_u32 s17, s17, 0
	s_cmp_gt_u32 s18, 13
	s_waitcnt vmcnt(6)
	s_barrier
	v_mfma_f32_16x16x32_bf16 v[64:67], v[208:211], v[160:163], v[64:67]
	v_mfma_f32_16x16x32_bf16 v[56:59], v[216:219], v[160:163], v[56:59]
	v_mfma_f32_16x16x32_bf16 v[48:51], v[208:211], v[172:175], v[48:51]
	v_mfma_f32_16x16x32_bf16 v[40:43], v[216:219], v[172:175], v[40:43]
	v_mfma_f32_16x16x32_bf16 v[32:35], v[208:211], v[180:183], v[32:35]
	v_mfma_f32_16x16x32_bf16 v[24:27], v[216:219], v[180:183], v[24:27]
	v_mfma_f32_16x16x32_bf16 v[16:19], v[208:211], v[200:203], v[16:19]
	v_mfma_f32_16x16x32_bf16 v[8:11], v[216:219], v[200:203], v[8:11]
	v_mfma_f32_16x16x32_bf16 v[64:67], v[212:215], v[164:167], v[64:67]
	v_mfma_f32_16x16x32_bf16 v[56:59], v[220:223], v[164:167], v[56:59]
	v_mfma_f32_16x16x32_bf16 v[48:51], v[212:215], v[176:179], v[48:51]
	v_mfma_f32_16x16x32_bf16 v[40:43], v[220:223], v[176:179], v[40:43]
	v_mfma_f32_16x16x32_bf16 v[32:35], v[212:215], v[196:199], v[32:35]
	v_mfma_f32_16x16x32_bf16 v[24:27], v[220:223], v[196:199], v[24:27]
	v_mfma_f32_16x16x32_bf16 v[16:19], v[212:215], v[204:207], v[16:19]
	v_mfma_f32_16x16x32_bf16 v[8:11], v[220:223], v[204:207], v[8:11]
	s_barrier
	s_cbranch_scc0 .LBB0_1120
	v_readfirstlane_b32 s2, v148
	s_lshr_b32 s4, s2, 1
	s_and_b32 s4, s4, 0x60
	v_lshrrev_b32_e32 v0, 1, v148
	v_and_or_b32 v0, v0, 24, s4
	v_and_b32_e32 v140, 15, v148
	s_lshl_b32 s4, s38, 10
	s_and_b32 s3, s2, 0xffffff00
	s_add_i32 s4, s4, s3
	v_lshl_add_u32 v141, v140, 2, s4
	v_add_u32_e32 v141, 0x20010, v141
	ds_read_b32 v240, v141
	ds_read_b32 v242, v141 offset:64
	ds_read_b32 v244, v141 offset:128
	ds_read_b32 v246, v141 offset:192
	ds_read_b32 v248, v141 offset:512
	ds_read_b32 v250, v141 offset:576
	ds_read_b32 v252, v141 offset:640
	ds_read_b32 v254, v141 offset:704
	s_ashr_i32 s3, s2, 2
	s_andn2_b32 s3, s3, 63
	v_or_b32_e32 v140, s3, v140
	v_lshl_add_u32 v140, s37, 8, v140
	v_mul_lo_u32 v140, v140, s76
	s_lshl_b32 s3, s33, 8
	v_lshlrev_b32_e32 v0, 1, v0
	v_add3_u32 v140, v140, v0, s3
	s_mov_b64 s[4:5], s[6:7]
	s_mov_b32 s2, 0xbfb8aa3b
	s_mov_b32 s100, 1.0
	s_waitcnt lgkmcnt(0)
	v_pk_mul_f32 v[132:133], v[132:133], v[240:241] op_sel_hi:[1,0]
	v_pk_mul_f32 v[128:129], v[128:129], v[240:241] op_sel_hi:[1,0]
	v_pk_mul_f32 v[216:217], v[132:133], s[2:3] op_sel_hi:[1,0]
	v_pk_mul_f32 v[134:135], v[134:135], v[240:241] op_sel_hi:[1,0]
	v_pk_mul_f32 v[130:131], v[130:131], v[240:241] op_sel_hi:[1,0]
	v_pk_mul_f32 v[218:219], v[134:135], s[2:3] op_sel_hi:[1,0]
	v_pk_mul_f32 v[124:125], v[124:125], v[240:241] op_sel_hi:[1,0]
	v_pk_mul_f32 v[120:121], v[120:121], v[240:241] op_sel_hi:[1,0]
	v_pk_mul_f32 v[220:221], v[124:125], s[2:3] op_sel_hi:[1,0]
	v_pk_mul_f32 v[126:127], v[126:127], v[240:241] op_sel_hi:[1,0]
	v_pk_mul_f32 v[122:123], v[122:123], v[240:241] op_sel_hi:[1,0]
	v_pk_mul_f32 v[222:223], v[126:127], s[2:3] op_sel_hi:[1,0]
	v_exp_f32_e32 v216, v216
	v_exp_f32_e32 v217, v217
	v_exp_f32_e32 v218, v218
	v_exp_f32_e32 v219, v219
	v_exp_f32_e32 v220, v220
	v_exp_f32_e32 v221, v221
	v_exp_f32_e32 v222, v222
	v_exp_f32_e32 v223, v223
	v_pk_add_f32 v[216:217], v[216:217], s[100:101] op_sel_hi:[1,0]
	v_pk_add_f32 v[218:219], v[218:219], s[100:101] op_sel_hi:[1,0]
	v_pk_add_f32 v[220:221], v[220:221], s[100:101] op_sel_hi:[1,0]
	v_pk_add_f32 v[222:223], v[222:223], s[100:101] op_sel_hi:[1,0]
	v_rcp_f32_e32 v216, v216
	v_rcp_f32_e32 v217, v217
	v_rcp_f32_e32 v218, v218
	v_rcp_f32_e32 v219, v219
	v_rcp_f32_e32 v220, v220
	v_rcp_f32_e32 v221, v221
	v_rcp_f32_e32 v222, v222
	v_rcp_f32_e32 v223, v223
	v_pk_mul_f32 v[132:133], v[132:133], v[216:217]
	v_pk_mul_f32 v[134:135], v[134:135], v[218:219]
	v_pk_mul_f32 v[124:125], v[124:125], v[220:221]
	v_pk_mul_f32 v[126:127], v[126:127], v[222:223]
	v_pk_mul_f32 v[132:133], v[132:133], v[128:129]
	v_pk_mul_f32 v[134:135], v[134:135], v[130:131]
	v_pk_mul_f32 v[124:125], v[124:125], v[120:121]
	v_pk_mul_f32 v[126:127], v[126:127], v[122:123]
	v_cvt_pk_bf16_f32 v236, v132, v133
	v_cvt_pk_bf16_f32 v237, v134, v135
	v_cvt_pk_bf16_f32 v238, v124, v125
	v_cvt_pk_bf16_f32 v239, v126, v127
	global_store_dwordx4 v140, v[236:239], s[4:5]
; __device__ __forceinline__ float sigmoidf_(float v) { return __builtin_amdgcn_rcpf(1.0f + __expf(-v)); }
; __device__ __forceinline__ u32x4 pack8(const f32x4 a, const f32x4 b) { u32x4 w; w.x = cvt_pk_bf16(a[0], a[1]); w.y = cvt_pk_bf16(a[2], a[3]); w.z = cvt_pk_bf16(b[0], b[1]); w.w = cvt_pk_bf16(b[2], b[3]); return w; }
; #define MEMFENCE asm volatile("" ::: "memory")
;     template <int KIND> __device__ __forceinline__ void run(f32x4 (&acc)[2][2][4][2], const Unit& u, int tid_in) const {
;     ...
;         if constexpr (KIND == K_FFI) { bf16_t* act = zb; float rs[8]; get_rs(u, wr, fr, rs);
; #pragma unroll
;             for (int ai = 0; ai < 2; ++ai)
; #pragma unroll
;                 for (int m = 0; m < 4; ++m) { int row = rbase + ai * 128 + m * 16; asm volatile("" : "+v"(row)); const float r = rs[ai * 4 + m]; f32x4 o[2];
; #pragma unroll
;                     for (int n = 0; n < 2; ++n) { const f32x4 g = acc[ai][0][m][n] * r, v = acc[ai][1][m][n] * r;
; #pragma unroll
;                         for (int j = 0; j < 4; ++j) o[n][j] = g[j] * sigmoidf_(g[j]) * v[j]; }
;                     *(u32x4*)(act + (size_t)row * ZW + u.pn * 128 + cl) = pack8(o[0], o[1]); MEMFENCE; }
	s_add_u32 s4, s4, 0x16000
	s_addc_u32 s5, s5, 0
	v_pk_mul_f32 v[116:117], v[116:117], v[242:243] op_sel_hi:[1,0]
	v_pk_mul_f32 v[112:113], v[112:113], v[242:243] op_sel_hi:[1,0]
	v_pk_mul_f32 v[216:217], v[116:117], s[2:3] op_sel_hi:[1,0]
	v_pk_mul_f32 v[118:119], v[118:119], v[242:243] op_sel_hi:[1,0]
	v_pk_mul_f32 v[114:115], v[114:115], v[242:243] op_sel_hi:[1,0]
	v_pk_mul_f32 v[218:219], v[118:119], s[2:3] op_sel_hi:[1,0]
	v_pk_mul_f32 v[108:109], v[108:109], v[242:243] op_sel_hi:[1,0]
	v_pk_mul_f32 v[104:105], v[104:105], v[242:243] op_sel_hi:[1,0]
	v_pk_mul_f32 v[220:221], v[108:109], s[2:3] op_sel_hi:[1,0]
	v_pk_mul_f32 v[110:111], v[110:111], v[242:243] op_sel_hi:[1,0]
	v_pk_mul_f32 v[106:107], v[106:107], v[242:243] op_sel_hi:[1,0]
	v_pk_mul_f32 v[222:223], v[110:111], s[2:3] op_sel_hi:[1,0]
	v_exp_f32_e32 v216, v216
	v_exp_f32_e32 v217, v217
	v_exp_f32_e32 v218, v218
	v_exp_f32_e32 v219, v219
	v_exp_f32_e32 v220, v220
	v_exp_f32_e32 v221, v221
	v_exp_f32_e32 v222, v222
	v_exp_f32_e32 v223, v223
	v_pk_add_f32 v[216:217], v[216:217], s[100:101] op_sel_hi:[1,0]
	v_pk_add_f32 v[218:219], v[218:219], s[100:101] op_sel_hi:[1,0]
	v_pk_add_f32 v[220:221], v[220:221], s[100:101] op_sel_hi:[1,0]
	v_pk_add_f32 v[222:223], v[222:223], s[100:101] op_sel_hi:[1,0]
	v_rcp_f32_e32 v216, v216
	v_rcp_f32_e32 v217, v217
	v_rcp_f32_e32 v218, v218
	v_rcp_f32_e32 v219, v219
	v_rcp_f32_e32 v220, v220
	v_rcp_f32_e32 v221, v221
	v_rcp_f32_e32 v222, v222
	v_rcp_f32_e32 v223, v223
	v_pk_mul_f32 v[116:117], v[116:117], v[216:217]
	v_pk_mul_f32 v[118:119], v[118:119], v[218:219]
	v_pk_mul_f32 v[108:109], v[108:109], v[220:221]
	v_pk_mul_f32 v[110:111], v[110:111], v[222:223]
	v_pk_mul_f32 v[116:117], v[116:117], v[112:113]
	v_pk_mul_f32 v[118:119], v[118:119], v[114:115]
	v_pk_mul_f32 v[108:109], v[108:109], v[104:105]
	v_pk_mul_f32 v[110:111], v[110:111], v[106:107]
	v_cvt_pk_bf16_f32 v236, v116, v117
	v_cvt_pk_bf16_f32 v237, v118, v119
	v_cvt_pk_bf16_f32 v238, v108, v109
	v_cvt_pk_bf16_f32 v239, v110, v111
	global_store_dwordx4 v140, v[236:239], s[4:5]
	s_add_u32 s4, s4, 0x16000
	s_addc_u32 s5, s5, 0
	v_pk_mul_f32 v[100:101], v[100:101], v[244:245] op_sel_hi:[1,0]
	v_pk_mul_f32 v[96:97], v[96:97], v[244:245] op_sel_hi:[1,0]
	v_pk_mul_f32 v[216:217], v[100:101], s[2:3] op_sel_hi:[1,0]
	v_pk_mul_f32 v[102:103], v[102:103], v[244:245] op_sel_hi:[1,0]
	v_pk_mul_f32 v[98:99], v[98:99], v[244:245] op_sel_hi:[1,0]
	v_pk_mul_f32 v[218:219], v[102:103], s[2:3] op_sel_hi:[1,0]
	v_pk_mul_f32 v[92:93], v[92:93], v[244:245] op_sel_hi:[1,0]
	v_pk_mul_f32 v[88:89], v[88:89], v[244:245] op_sel_hi:[1,0]
	v_pk_mul_f32 v[220:221], v[92:93], s[2:3] op_sel_hi:[1,0]
	v_pk_mul_f32 v[94:95], v[94:95], v[244:245] op_sel_hi:[1,0]
	v_pk_mul_f32 v[90:91], v[90:91], v[244:245] op_sel_hi:[1,0]
	v_pk_mul_f32 v[222:223], v[94:95], s[2:3] op_sel_hi:[1,0]
	v_exp_f32_e32 v216, v216
	v_exp_f32_e32 v217, v217
	v_exp_f32_e32 v218, v218
	v_exp_f32_e32 v219, v219
	v_exp_f32_e32 v220, v220
	v_exp_f32_e32 v221, v221
	v_exp_f32_e32 v222, v222
	v_exp_f32_e32 v223, v223
	v_pk_add_f32 v[216:217], v[216:217], s[100:101] op_sel_hi:[1,0]
	v_pk_add_f32 v[218:219], v[218:219], s[100:101] op_sel_hi:[1,0]
	v_pk_add_f32 v[220:221], v[220:221], s[100:101] op_sel_hi:[1,0]
	v_pk_add_f32 v[222:223], v[222:223], s[100:101] op_sel_hi:[1,0]
	v_rcp_f32_e32 v216, v216
	v_rcp_f32_e32 v217, v217
	v_rcp_f32_e32 v218, v218
	v_rcp_f32_e32 v219, v219
	v_rcp_f32_e32 v220, v220
	v_rcp_f32_e32 v221, v221
	v_rcp_f32_e32 v222, v222
	v_rcp_f32_e32 v223, v223
	v_pk_mul_f32 v[100:101], v[100:101], v[216:217]
	v_pk_mul_f32 v[102:103], v[102:103], v[218:219]
	v_pk_mul_f32 v[92:93], v[92:93], v[220:221]
	v_pk_mul_f32 v[94:95], v[94:95], v[222:223]
	v_pk_mul_f32 v[100:101], v[100:101], v[96:97]
	v_pk_mul_f32 v[102:103], v[102:103], v[98:99]
	v_pk_mul_f32 v[92:93], v[92:93], v[88:89]
	v_pk_mul_f32 v[94:95], v[94:95], v[90:91]
	v_cvt_pk_bf16_f32 v236, v100, v101
	v_cvt_pk_bf16_f32 v237, v102, v103
	v_cvt_pk_bf16_f32 v238, v92, v93
	v_cvt_pk_bf16_f32 v239, v94, v95
	global_store_dwordx4 v140, v[236:239], s[4:5]
	s_add_u32 s4, s4, 0x16000
	s_addc_u32 s5, s5, 0
	v_pk_mul_f32 v[84:85], v[84:85], v[246:247] op_sel_hi:[1,0]
	v_pk_mul_f32 v[80:81], v[80:81], v[246:247] op_sel_hi:[1,0]
	v_pk_mul_f32 v[216:217], v[84:85], s[2:3] op_sel_hi:[1,0]
	v_pk_mul_f32 v[86:87], v[86:87], v[246:247] op_sel_hi:[1,0]
	v_pk_mul_f32 v[82:83], v[82:83], v[246:247] op_sel_hi:[1,0]
	v_pk_mul_f32 v[218:219], v[86:87], s[2:3] op_sel_hi:[1,0]
	v_pk_mul_f32 v[76:77], v[76:77], v[246:247] op_sel_hi:[1,0]
	v_pk_mul_f32 v[72:73], v[72:73], v[246:247] op_sel_hi:[1,0]
	v_pk_mul_f32 v[220:221], v[76:77], s[2:3] op_sel_hi:[1,0]
	v_pk_mul_f32 v[78:79], v[78:79], v[246:247] op_sel_hi:[1,0]
	v_pk_mul_f32 v[74:75], v[74:75], v[246:247] op_sel_hi:[1,0]
	v_pk_mul_f32 v[222:223], v[78:79], s[2:3] op_sel_hi:[1,0]
	v_exp_f32_e32 v216, v216
	v_exp_f32_e32 v217, v217
	v_exp_f32_e32 v218, v218
	v_exp_f32_e32 v219, v219
	v_exp_f32_e32 v220, v220
	v_exp_f32_e32 v221, v221
	v_exp_f32_e32 v222, v222
	v_exp_f32_e32 v223, v223
	v_pk_add_f32 v[216:217], v[216:217], s[100:101] op_sel_hi:[1,0]
	v_pk_add_f32 v[218:219], v[218:219], s[100:101] op_sel_hi:[1,0]
	v_pk_add_f32 v[220:221], v[220:221], s[100:101] op_sel_hi:[1,0]
	v_pk_add_f32 v[222:223], v[222:223], s[100:101] op_sel_hi:[1,0]
	v_rcp_f32_e32 v216, v216
	v_rcp_f32_e32 v217, v217
	v_rcp_f32_e32 v218, v218
	v_rcp_f32_e32 v219, v219
	v_rcp_f32_e32 v220, v220
	v_rcp_f32_e32 v221, v221
	v_rcp_f32_e32 v222, v222
	v_rcp_f32_e32 v223, v223
	v_pk_mul_f32 v[84:85], v[84:85], v[216:217]
	v_pk_mul_f32 v[86:87], v[86:87], v[218:219]
; __device__ __forceinline__ float sigmoidf_(float v) { return __builtin_amdgcn_rcpf(1.0f + __expf(-v)); }
; __device__ __forceinline__ u32x4 pack8(const f32x4 a, const f32x4 b) { u32x4 w; w.x = cvt_pk_bf16(a[0], a[1]); w.y = cvt_pk_bf16(a[2], a[3]); w.z = cvt_pk_bf16(b[0], b[1]); w.w = cvt_pk_bf16(b[2], b[3]); return w; }
; #define MEMFENCE asm volatile("" ::: "memory")
;     template <int KIND> __device__ __forceinline__ void run(f32x4 (&acc)[2][2][4][2], const Unit& u, int tid_in) const {
;     ...
;         if constexpr (KIND == K_FFI) { bf16_t* act = zb; float rs[8]; get_rs(u, wr, fr, rs);
; #pragma unroll
;             for (int ai = 0; ai < 2; ++ai)
; #pragma unroll
;                 for (int m = 0; m < 4; ++m) { int row = rbase + ai * 128 + m * 16; asm volatile("" : "+v"(row)); const float r = rs[ai * 4 + m]; f32x4 o[2];
; #pragma unroll
;                     for (int n = 0; n < 2; ++n) { const f32x4 g = acc[ai][0][m][n] * r, v = acc[ai][1][m][n] * r;
; #pragma unroll
;                         for (int j = 0; j < 4; ++j) o[n][j] = g[j] * sigmoidf_(g[j]) * v[j]; }
;                     *(u32x4*)(act + (size_t)row * ZW + u.pn * 128 + cl) = pack8(o[0], o[1]); MEMFENCE; }
	v_pk_mul_f32 v[76:77], v[76:77], v[220:221]
	v_pk_mul_f32 v[78:79], v[78:79], v[222:223]
	v_pk_mul_f32 v[84:85], v[84:85], v[80:81]
	v_pk_mul_f32 v[86:87], v[86:87], v[82:83]
	v_pk_mul_f32 v[76:77], v[76:77], v[72:73]
	v_pk_mul_f32 v[78:79], v[78:79], v[74:75]
	v_cvt_pk_bf16_f32 v236, v84, v85
	v_cvt_pk_bf16_f32 v237, v86, v87
	v_cvt_pk_bf16_f32 v238, v76, v77
	v_cvt_pk_bf16_f32 v239, v78, v79
	global_store_dwordx4 v140, v[236:239], s[4:5]
	s_add_u32 s4, s4, 0x6e000
	s_addc_u32 s5, s5, 0
	v_pk_mul_f32 v[68:69], v[68:69], v[248:249] op_sel_hi:[1,0]
	v_pk_mul_f32 v[64:65], v[64:65], v[248:249] op_sel_hi:[1,0]
	v_pk_mul_f32 v[216:217], v[68:69], s[2:3] op_sel_hi:[1,0]
	v_pk_mul_f32 v[70:71], v[70:71], v[248:249] op_sel_hi:[1,0]
	v_pk_mul_f32 v[66:67], v[66:67], v[248:249] op_sel_hi:[1,0]
	v_pk_mul_f32 v[218:219], v[70:71], s[2:3] op_sel_hi:[1,0]
	v_pk_mul_f32 v[60:61], v[60:61], v[248:249] op_sel_hi:[1,0]
	v_pk_mul_f32 v[56:57], v[56:57], v[248:249] op_sel_hi:[1,0]
	v_pk_mul_f32 v[220:221], v[60:61], s[2:3] op_sel_hi:[1,0]
	v_pk_mul_f32 v[62:63], v[62:63], v[248:249] op_sel_hi:[1,0]
	v_pk_mul_f32 v[58:59], v[58:59], v[248:249] op_sel_hi:[1,0]
	v_pk_mul_f32 v[222:223], v[62:63], s[2:3] op_sel_hi:[1,0]
	v_exp_f32_e32 v216, v216
	v_exp_f32_e32 v217, v217
	v_exp_f32_e32 v218, v218
	v_exp_f32_e32 v219, v219
	v_exp_f32_e32 v220, v220
	v_exp_f32_e32 v221, v221
	v_exp_f32_e32 v222, v222
	v_exp_f32_e32 v223, v223
	v_pk_add_f32 v[216:217], v[216:217], s[100:101] op_sel_hi:[1,0]
	v_pk_add_f32 v[218:219], v[218:219], s[100:101] op_sel_hi:[1,0]
	v_pk_add_f32 v[220:221], v[220:221], s[100:101] op_sel_hi:[1,0]
	v_pk_add_f32 v[222:223], v[222:223], s[100:101] op_sel_hi:[1,0]
	v_rcp_f32_e32 v216, v216
	v_rcp_f32_e32 v217, v217
	v_rcp_f32_e32 v218, v218
	v_rcp_f32_e32 v219, v219
	v_rcp_f32_e32 v220, v220
	v_rcp_f32_e32 v221, v221
	v_rcp_f32_e32 v222, v222
	v_rcp_f32_e32 v223, v223
	v_pk_mul_f32 v[68:69], v[68:69], v[216:217]
	v_pk_mul_f32 v[70:71], v[70:71], v[218:219]
	v_pk_mul_f32 v[60:61], v[60:61], v[220:221]
	v_pk_mul_f32 v[62:63], v[62:63], v[222:223]
	v_pk_mul_f32 v[68:69], v[68:69], v[64:65]
	v_pk_mul_f32 v[70:71], v[70:71], v[66:67]
	v_pk_mul_f32 v[60:61], v[60:61], v[56:57]
	v_pk_mul_f32 v[62:63], v[62:63], v[58:59]
	v_cvt_pk_bf16_f32 v236, v68, v69
	v_cvt_pk_bf16_f32 v237, v70, v71
	v_cvt_pk_bf16_f32 v238, v60, v61
	v_cvt_pk_bf16_f32 v239, v62, v63
	global_store_dwordx4 v140, v[236:239], s[4:5]
	s_add_u32 s4, s4, 0x16000
	s_addc_u32 s5, s5, 0
	v_pk_mul_f32 v[52:53], v[52:53], v[250:251] op_sel_hi:[1,0]
	v_pk_mul_f32 v[48:49], v[48:49], v[250:251] op_sel_hi:[1,0]
	v_pk_mul_f32 v[216:217], v[52:53], s[2:3] op_sel_hi:[1,0]
	v_pk_mul_f32 v[54:55], v[54:55], v[250:251] op_sel_hi:[1,0]
	v_pk_mul_f32 v[50:51], v[50:51], v[250:251] op_sel_hi:[1,0]
	v_pk_mul_f32 v[218:219], v[54:55], s[2:3] op_sel_hi:[1,0]
	v_pk_mul_f32 v[44:45], v[44:45], v[250:251] op_sel_hi:[1,0]
	v_pk_mul_f32 v[40:41], v[40:41], v[250:251] op_sel_hi:[1,0]
	v_pk_mul_f32 v[220:221], v[44:45], s[2:3] op_sel_hi:[1,0]
	v_pk_mul_f32 v[46:47], v[46:47], v[250:251] op_sel_hi:[1,0]
	v_pk_mul_f32 v[42:43], v[42:43], v[250:251] op_sel_hi:[1,0]
	v_pk_mul_f32 v[222:223], v[46:47], s[2:3] op_sel_hi:[1,0]
	v_exp_f32_e32 v216, v216
	v_exp_f32_e32 v217, v217
	v_exp_f32_e32 v218, v218
	v_exp_f32_e32 v219, v219
	v_exp_f32_e32 v220, v220
	v_exp_f32_e32 v221, v221
	v_exp_f32_e32 v222, v222
	v_exp_f32_e32 v223, v223
	v_pk_add_f32 v[216:217], v[216:217], s[100:101] op_sel_hi:[1,0]
	v_pk_add_f32 v[218:219], v[218:219], s[100:101] op_sel_hi:[1,0]
	v_pk_add_f32 v[220:221], v[220:221], s[100:101] op_sel_hi:[1,0]
	v_pk_add_f32 v[222:223], v[222:223], s[100:101] op_sel_hi:[1,0]
	v_rcp_f32_e32 v216, v216
	v_rcp_f32_e32 v217, v217
	v_rcp_f32_e32 v218, v218
	v_rcp_f32_e32 v219, v219
	v_rcp_f32_e32 v220, v220
	v_rcp_f32_e32 v221, v221
	v_rcp_f32_e32 v222, v222
	v_rcp_f32_e32 v223, v223
	v_pk_mul_f32 v[52:53], v[52:53], v[216:217]
	v_pk_mul_f32 v[54:55], v[54:55], v[218:219]
	v_pk_mul_f32 v[44:45], v[44:45], v[220:221]
	v_pk_mul_f32 v[46:47], v[46:47], v[222:223]
	v_pk_mul_f32 v[52:53], v[52:53], v[48:49]
	v_pk_mul_f32 v[54:55], v[54:55], v[50:51]
	v_pk_mul_f32 v[44:45], v[44:45], v[40:41]
	v_pk_mul_f32 v[46:47], v[46:47], v[42:43]
	v_cvt_pk_bf16_f32 v236, v52, v53
	v_cvt_pk_bf16_f32 v237, v54, v55
	v_cvt_pk_bf16_f32 v238, v44, v45
; __device__ __forceinline__ float sigmoidf_(float v) { return __builtin_amdgcn_rcpf(1.0f + __expf(-v)); }
; __device__ __forceinline__ u32x4 pack8(const f32x4 a, const f32x4 b) { u32x4 w; w.x = cvt_pk_bf16(a[0], a[1]); w.y = cvt_pk_bf16(a[2], a[3]); w.z = cvt_pk_bf16(b[0], b[1]); w.w = cvt_pk_bf16(b[2], b[3]); return w; }
; #define MEMFENCE asm volatile("" ::: "memory")
; #define G_WAIT_V(n) asm volatile("s_waitcnt vmcnt(" #n ")" ::: "memory")
; #define G_BAR __builtin_amdgcn_s_barrier()
;     template <int KIND> __device__ __forceinline__ void run(f32x4 (&acc)[2][2][4][2], const Unit& u, int tid_in) const {
;     ...
;         if constexpr (KIND == K_FFI) { bf16_t* act = zb; float rs[8]; get_rs(u, wr, fr, rs);
; #pragma unroll
;             for (int ai = 0; ai < 2; ++ai)
; #pragma unroll
;                 for (int m = 0; m < 4; ++m) { int row = rbase + ai * 128 + m * 16; asm volatile("" : "+v"(row)); const float r = rs[ai * 4 + m]; f32x4 o[2];
; #pragma unroll
;                     for (int n = 0; n < 2; ++n) { const f32x4 g = acc[ai][0][m][n] * r, v = acc[ai][1][m][n] * r;
; #pragma unroll
;                         for (int j = 0; j < 4; ++j) o[n][j] = g[j] * sigmoidf_(g[j]) * v[j]; }
;                     *(u32x4*)(act + (size_t)row * ZW + u.pn * 128 + cl) = pack8(o[0], o[1]); MEMFENCE; }
;     ...
;         cur = nxt; cA = nA; cB = nB; ++ui;
;     }
;     G_WAIT_V(0);
;     if (wr == 0) G_BAR;
;     G_BAR;
	v_cvt_pk_bf16_f32 v239, v46, v47
	global_store_dwordx4 v140, v[236:239], s[4:5]
	s_add_u32 s4, s4, 0x16000
	s_addc_u32 s5, s5, 0
	v_pk_mul_f32 v[36:37], v[36:37], v[252:253] op_sel_hi:[1,0]
	v_pk_mul_f32 v[32:33], v[32:33], v[252:253] op_sel_hi:[1,0]
	v_pk_mul_f32 v[216:217], v[36:37], s[2:3] op_sel_hi:[1,0]
	v_pk_mul_f32 v[38:39], v[38:39], v[252:253] op_sel_hi:[1,0]
	v_pk_mul_f32 v[34:35], v[34:35], v[252:253] op_sel_hi:[1,0]
	v_pk_mul_f32 v[218:219], v[38:39], s[2:3] op_sel_hi:[1,0]
	v_pk_mul_f32 v[28:29], v[28:29], v[252:253] op_sel_hi:[1,0]
	v_pk_mul_f32 v[24:25], v[24:25], v[252:253] op_sel_hi:[1,0]
	v_pk_mul_f32 v[220:221], v[28:29], s[2:3] op_sel_hi:[1,0]
	v_pk_mul_f32 v[30:31], v[30:31], v[252:253] op_sel_hi:[1,0]
	v_pk_mul_f32 v[26:27], v[26:27], v[252:253] op_sel_hi:[1,0]
	v_pk_mul_f32 v[222:223], v[30:31], s[2:3] op_sel_hi:[1,0]
	v_exp_f32_e32 v216, v216
	v_exp_f32_e32 v217, v217
	v_exp_f32_e32 v218, v218
	v_exp_f32_e32 v219, v219
	v_exp_f32_e32 v220, v220
	v_exp_f32_e32 v221, v221
	v_exp_f32_e32 v222, v222
	v_exp_f32_e32 v223, v223
	v_pk_add_f32 v[216:217], v[216:217], s[100:101] op_sel_hi:[1,0]
	v_pk_add_f32 v[218:219], v[218:219], s[100:101] op_sel_hi:[1,0]
	v_pk_add_f32 v[220:221], v[220:221], s[100:101] op_sel_hi:[1,0]
	v_pk_add_f32 v[222:223], v[222:223], s[100:101] op_sel_hi:[1,0]
	v_rcp_f32_e32 v216, v216
	v_rcp_f32_e32 v217, v217
	v_rcp_f32_e32 v218, v218
	v_rcp_f32_e32 v219, v219
	v_rcp_f32_e32 v220, v220
	v_rcp_f32_e32 v221, v221
	v_rcp_f32_e32 v222, v222
	v_rcp_f32_e32 v223, v223
	v_pk_mul_f32 v[36:37], v[36:37], v[216:217]
	v_pk_mul_f32 v[38:39], v[38:39], v[218:219]
	v_pk_mul_f32 v[28:29], v[28:29], v[220:221]
	v_pk_mul_f32 v[30:31], v[30:31], v[222:223]
	v_pk_mul_f32 v[36:37], v[36:37], v[32:33]
	v_pk_mul_f32 v[38:39], v[38:39], v[34:35]
	v_pk_mul_f32 v[28:29], v[28:29], v[24:25]
	v_pk_mul_f32 v[30:31], v[30:31], v[26:27]
	v_cvt_pk_bf16_f32 v236, v36, v37
	v_cvt_pk_bf16_f32 v237, v38, v39
	v_cvt_pk_bf16_f32 v238, v28, v29
	v_cvt_pk_bf16_f32 v239, v30, v31
	global_store_dwordx4 v140, v[236:239], s[4:5]
	s_add_u32 s4, s4, 0x16000
	s_addc_u32 s5, s5, 0
	v_pk_mul_f32 v[20:21], v[20:21], v[254:255] op_sel_hi:[1,0]
	v_pk_mul_f32 v[16:17], v[16:17], v[254:255] op_sel_hi:[1,0]
	v_pk_mul_f32 v[216:217], v[20:21], s[2:3] op_sel_hi:[1,0]
	v_pk_mul_f32 v[22:23], v[22:23], v[254:255] op_sel_hi:[1,0]
	v_pk_mul_f32 v[18:19], v[18:19], v[254:255] op_sel_hi:[1,0]
	v_pk_mul_f32 v[218:219], v[22:23], s[2:3] op_sel_hi:[1,0]
	v_pk_mul_f32 v[12:13], v[12:13], v[254:255] op_sel_hi:[1,0]
	v_pk_mul_f32 v[8:9], v[8:9], v[254:255] op_sel_hi:[1,0]
	v_pk_mul_f32 v[220:221], v[12:13], s[2:3] op_sel_hi:[1,0]
	v_pk_mul_f32 v[14:15], v[14:15], v[254:255] op_sel_hi:[1,0]
	v_pk_mul_f32 v[10:11], v[10:11], v[254:255] op_sel_hi:[1,0]
	v_pk_mul_f32 v[222:223], v[14:15], s[2:3] op_sel_hi:[1,0]
	v_exp_f32_e32 v216, v216
	v_exp_f32_e32 v217, v217
	v_exp_f32_e32 v218, v218
	v_exp_f32_e32 v219, v219
	v_exp_f32_e32 v220, v220
	v_exp_f32_e32 v221, v221
	v_exp_f32_e32 v222, v222
	v_exp_f32_e32 v223, v223
	v_pk_add_f32 v[216:217], v[216:217], s[100:101] op_sel_hi:[1,0]
	v_pk_add_f32 v[218:219], v[218:219], s[100:101] op_sel_hi:[1,0]
	v_pk_add_f32 v[220:221], v[220:221], s[100:101] op_sel_hi:[1,0]
	v_pk_add_f32 v[222:223], v[222:223], s[100:101] op_sel_hi:[1,0]
	v_rcp_f32_e32 v216, v216
	v_rcp_f32_e32 v217, v217
	v_rcp_f32_e32 v218, v218
	v_rcp_f32_e32 v219, v219
	v_rcp_f32_e32 v220, v220
	v_rcp_f32_e32 v221, v221
	v_rcp_f32_e32 v222, v222
	v_rcp_f32_e32 v223, v223
	v_pk_mul_f32 v[20:21], v[20:21], v[216:217]
	v_pk_mul_f32 v[22:23], v[22:23], v[218:219]
	v_pk_mul_f32 v[12:13], v[12:13], v[220:221]
	v_pk_mul_f32 v[14:15], v[14:15], v[222:223]
	v_pk_mul_f32 v[20:21], v[20:21], v[16:17]
	v_pk_mul_f32 v[22:23], v[22:23], v[18:19]
	v_pk_mul_f32 v[12:13], v[12:13], v[8:9]
	v_pk_mul_f32 v[14:15], v[14:15], v[10:11]
	v_cvt_pk_bf16_f32 v236, v20, v21
	v_cvt_pk_bf16_f32 v237, v22, v23
	v_cvt_pk_bf16_f32 v238, v12, v13
	v_cvt_pk_bf16_f32 v239, v14, v15
	global_store_dwordx4 v140, v[236:239], s[4:5]
	s_mov_b32 s38, s11
	s_mov_b32 s37, s10
	s_mov_b64 s[18:19], s[14:15]
	s_mov_b64 s[16:17], s[12:13]
	s_mov_b32 s33, s36
	s_and_b64 vcc, exec, s[8:9]
	s_cbranch_vccz .LBB0_1115
	s_waitcnt vmcnt(0)
	s_cmpk_gt_u32 s20, 0xff
	s_cbranch_scc1 .LBB0_1124
	s_barrier
